# SWA items: the 20 V-tile loads of the PV step issued together once the V base is known (were 20 load / wait / MFMA round trips)
# baseline (speedup 1.0000x reference)
; #define MFMA32(a, b, c) __builtin_amdgcn_mfma_f32_32x32x16_bf16((a), (b), (c), 0, 0, 0)
; DI int crow(int r, int h) { return (r & 3) + 8 * (r >> 2) + 4 * h; }
; DI void swa_item(const Params& p, int item, int lane) {
;     ...
;   const int w = item & 3, hq = (item >> 2) & 7, n = (item >> 5) & 63, b = item >> 11;
;   const int g = hq >> 2;
;   const float slope = exp2f(-(float)(hq + 1)) * LOG2E;
;   const float sink = p.sinks[hq] * LOG2E;
;   const int qi = 32 * w + l31;
;   const int token = b * SEQ + n * 128 + qi;
;   bf16x8 qf[4];
; #pragma unroll
;   for (int s = 0; s < 4; ++s) qf[s] = ldg8(proj + (size_t)token * INC + hq * 64 + 16 * s + 8 * h);
;   const bf16_t* kbase = proj + (size_t)(b * SEQ) * INC + 512 + g * 64 + 8 * h;
;   f32x16 sc[5];
;   float m = sink;
;   bf16x8 kc[4], kn[4];
;   {
;     const int pos0 = (n - 1) * 128 + 32 * w, pc = pos0 < 0 ? 0 : pos0;
; #pragma unroll
;     for (int s = 0; s < 4; ++s) kc[s] = ldg8(kbase + (size_t)(pc + l31) * INC + 16 * s);
;   }
; #pragma unroll
;   for (int t = 0; t < 5; ++t) {
;     const int kj0 = 32 * (w + t);
;     const int pos0 = (n - 1) * 128 + kj0;
;     if (t < 4) {
;       const int pn = pos0 + 32, pc = pn < 0 ? 0 : pn;
; #pragma unroll
;       for (int s = 0; s < 4; ++s) kn[s] = ldg8(kbase + (size_t)(pc + l31) * INC + 16 * s);
;     }
;     f32x16 acc;
; #pragma unroll
;     for (int r = 0; r < 16; ++r) acc[r] = 0.f;
; #pragma unroll
;     for (int s = 0; s < 4; ++s) acc = MFMA32(kc[s], qf[s], acc);
;     const bool tile_ok = pos0 >= 0;
; #pragma unroll
;     for (int r = 0; r < 16; ++r) {
;       int dist = 128 + qi - (kj0 + crow(r, h));
;       bool valid = tile_ok && (dist >= 0) && (dist < 128);
;       float v = valid ? acc[r] - slope * (float)dist : -INFINITY;
;       sc[t][r] = v;
;       m = fmaxf(m, v);
;     }
; #pragma unroll
;     for (int s = 0; s < 4; ++s) kc[s] = kn[s];
;   }
.LBB0_246:
	s_movk_i32 s0, 0x1fff
	v_cmp_lt_i32_e32 vcc, s0, v83
	v_bfe_u32 v0, v83, 5, 6
	s_and_saveexec_b64 s[0:1], vcc
	s_xor_b64 s[42:43], exec, s[0:1]
	s_cbranch_execz .LBB0_250
	v_add_u32_e32 v1, 0xffffe000, v83
	v_bfe_u32 v4, v1, 2, 3
	v_add_u32_e32 v2, 1, v4
	v_cvt_f32_ubyte0_e32 v2, v2
	s_mov_b32 s0, 0x42fc0000
	v_cmp_lt_f32_e32 vcc, s0, v2
	v_lshrrev_b32_e32 v91, 11, v1
	v_lshlrev_b32_e32 v6, 7, v0
	v_cndmask_b32_e32 v3, 0, v140, vcc
	v_sub_f32_e32 v2, v3, v2
	v_exp_f32_e32 v2, v2
	v_cndmask_b32_e32 v3, 0, v141, vcc
	s_movk_i32 s0, 0x900
	v_lshlrev_b32_e32 v70, 7, v4
	v_ldexp_f32 v5, v2, v3
	v_lshlrev_b32_e32 v2, 5, v83
	v_and_b32_e32 v98, 0x60, v2
	v_or_b32_e32 v99, v98, v119
	v_lshlrev_b32_e32 v2, 13, v91
	v_or3_b32 v69, v6, v2, v99
	v_mul_lo_u32 v80, v69, s0
	v_lshl_add_u64 v[2:3], v[80:81], 1, s[48:49]
	v_mov_b32_e32 v71, v81
	v_lshl_add_u64 v[2:3], v[2:3], 0, v[70:71]
	v_mov_b32_e32 v89, v81
	s_mov_b32 s0, 0x1200000
	v_lshlrev_b32_e32 v1, 2, v1
	v_lshlrev_b32_e32 v68, 2, v4
	v_lshl_add_u64 v[2:3], v[2:3], 0, v[88:89]
	v_mul_lo_u32 v80, v91, s0
	v_and_b32_e32 v94, 64, v1
	global_load_dword v95, v68, s[82:83]
	global_load_dwordx4 v[28:31], v[2:3], off
	global_load_dwordx4 v[24:27], v[2:3], off offset:32
	global_load_dwordx4 v[16:19], v[2:3], off offset:64
	global_load_dwordx4 v[20:23], v[2:3], off offset:96
	v_lshl_add_u64 v[2:3], v[80:81], 1, s[48:49]
	v_lshlrev_b32_e32 v80, 1, v94
	v_lshl_add_u64 v[2:3], v[2:3], 0, v[80:81]
	v_add_u32_e32 v145, 0xffffff80, v6
	v_lshl_add_u64 v[72:73], v[2:3], 0, v[88:89]
	v_or_b32_e32 v89, v145, v98
	v_cmp_ne_u32_e32 vcc, 0, v0
	v_mul_f32_e32 v74, 0x3fb8aa3b, v5
	v_or_b32_e32 v117, 0x80, v99
	v_cndmask_b32_e32 v0, 0, v89, vcc
	v_or_b32_e32 v0, v0, v119
	v_mul_i32_i24_e32 v0, 0x900, v0
	v_ashrrev_i32_e32 v1, 31, v0
	v_lshl_add_u64 v[4:5], v[0:1], 1, v[72:73]
	global_load_dwordx4 v[0:3], v[4:5], off offset:1024
	global_load_dwordx4 v[50:53], v[4:5], off offset:1056
	global_load_dwordx4 v[54:57], v[4:5], off offset:1088
	global_load_dwordx4 v[58:61], v[4:5], off offset:1120
	v_max_i32_e32 v4, 0xffffffe0, v89
	v_add_u32_e32 v4, v4, v120
	v_mad_u64_u32 v[4:5], s[0:1], v4, s22, v[72:73]
	global_load_dwordx4 v[44:47], v[4:5], off offset:1024
	global_load_dwordx4 v[40:43], v[4:5], off offset:1056
	global_load_dwordx4 v[32:35], v[4:5], off offset:1088
	global_load_dwordx4 v[36:39], v[4:5], off offset:1120
	v_sub_u32_e32 v49, v117, v98
	v_add_u32_e32 v65, 32, v98
	v_add_u32_e32 v143, v145, v65
	s_waitcnt vmcnt(7)
	v_mfma_f32_32x32x16_bf16 v[0:15], v[0:3], v[28:31], 0
	v_mul_f32_e32 v48, 0x3fb8aa3b, v95
	s_waitcnt vmcnt(6)
	v_mfma_f32_32x32x16_bf16 v[0:15], v[50:53], v[24:27], v[0:15]
	v_add_u32_e32 v50, v49, v121
	v_cmp_gt_u32_e64 s[0:1], s21, v50
	v_cvt_f32_u32_e32 v50, v50
	s_and_b64 s[0:1], vcc, s[0:1]
	s_waitcnt vmcnt(5)
	v_mfma_f32_32x32x16_bf16 v[0:15], v[54:57], v[16:19], v[0:15]
	s_waitcnt vmcnt(4)
	v_mfma_f32_32x32x16_bf16 v[0:15], v[58:61], v[20:23], v[0:15]
	s_nop 11
	v_fma_f32 v0, -v74, v50, v0
	v_cndmask_b32_e64 v75, v142, v0, s[0:1]
	v_add_u32_e32 v0, v49, v122
	v_cmp_gt_u32_e64 s[0:1], s21, v0
	v_cvt_f32_u32_e32 v0, v0
	s_and_b64 s[0:1], vcc, s[0:1]
	v_fma_f32 v0, -v74, v0, v1
	v_cndmask_b32_e64 v76, v142, v0, s[0:1]
	v_add_u32_e32 v0, v49, v123
	v_cmp_gt_u32_e64 s[0:1], s21, v0
	v_cvt_f32_u32_e32 v0, v0
	s_and_b64 s[0:1], vcc, s[0:1]
	v_fma_f32 v0, -v74, v0, v2
	v_cndmask_b32_e64 v77, v142, v0, s[0:1]
	v_add_u32_e32 v0, v49, v124
	v_cmp_gt_u32_e64 s[0:1], s21, v0
	v_cvt_f32_u32_e32 v0, v0
	s_and_b64 s[0:1], vcc, s[0:1]
	v_fma_f32 v0, -v74, v0, v3
	v_cndmask_b32_e64 v78, v142, v0, s[0:1]
	v_add_u32_e32 v0, v49, v125
	v_cmp_gt_u32_e64 s[0:1], s21, v0
	v_cvt_f32_u32_e32 v0, v0
	s_and_b64 s[0:1], vcc, s[0:1]
	v_fma_f32 v0, -v74, v0, v4
	v_cndmask_b32_e64 v79, v142, v0, s[0:1]
	v_add_u32_e32 v0, v49, v126
	v_cmp_gt_u32_e64 s[0:1], s21, v0
	v_cvt_f32_u32_e32 v0, v0
	s_and_b64 s[0:1], vcc, s[0:1]
	v_fma_f32 v0, -v74, v0, v5
	v_cndmask_b32_e64 v80, v142, v0, s[0:1]
	v_add_u32_e32 v0, v49, v127
	v_cmp_gt_u32_e64 s[0:1], s21, v0
	v_cvt_f32_u32_e32 v0, v0
	s_and_b64 s[0:1], vcc, s[0:1]
	v_fma_f32 v0, -v74, v0, v6
	v_cndmask_b32_e64 v92, v142, v0, s[0:1]
	v_add_u32_e32 v0, v49, v128
	v_cmp_gt_u32_e64 s[0:1], s21, v0
	v_cvt_f32_u32_e32 v0, v0
	s_and_b64 s[0:1], vcc, s[0:1]
	v_fma_f32 v0, -v74, v0, v7
	v_cndmask_b32_e64 v93, v142, v0, s[0:1]
	v_add_u32_e32 v0, v49, v129
	v_cmp_gt_u32_e64 s[0:1], s21, v0
	v_cvt_f32_u32_e32 v0, v0
	s_and_b64 s[0:1], vcc, s[0:1]
	v_fma_f32 v0, -v74, v0, v8
	v_cndmask_b32_e64 v96, v142, v0, s[0:1]
	v_add_u32_e32 v0, v49, v130
	v_cmp_gt_u32_e64 s[0:1], s21, v0
	v_cvt_f32_u32_e32 v0, v0
	s_and_b64 s[0:1], vcc, s[0:1]
	v_fma_f32 v0, -v74, v0, v9
	v_cndmask_b32_e64 v97, v142, v0, s[0:1]
	v_add_u32_e32 v0, v49, v131
	v_cmp_gt_u32_e64 s[0:1], s21, v0
	v_cvt_f32_u32_e32 v0, v0
	s_and_b64 s[40:41], vcc, s[0:1]
	v_fma_f32 v0, -v74, v0, v10
	v_cndmask_b32_e64 v100, v142, v0, s[40:41]
	v_add_u32_e32 v0, v49, v132
	v_cmp_gt_u32_e64 s[0:1], s21, v0
	v_cvt_f32_u32_e32 v0, v0
	s_and_b64 s[0:1], vcc, s[0:1]
	v_fma_f32 v0, -v74, v0, v11
	v_cndmask_b32_e64 v101, v142, v0, s[0:1]
	v_add_u32_e32 v0, v49, v133
	v_cmp_gt_u32_e64 s[0:1], s21, v0
	v_cvt_f32_u32_e32 v0, v0
	s_and_b64 s[0:1], vcc, s[0:1]
	v_fma_f32 v0, -v74, v0, v12
	v_cndmask_b32_e64 v102, v142, v0, s[0:1]
	v_add_u32_e32 v0, v49, v134
	v_cmp_gt_u32_e64 s[0:1], s21, v0
	v_cvt_f32_u32_e32 v0, v0
	s_and_b64 s[0:1], vcc, s[0:1]
	v_fma_f32 v0, -v74, v0, v13
	v_cndmask_b32_e64 v103, v142, v0, s[0:1]
	v_add_u32_e32 v0, v49, v135
	v_cmp_gt_u32_e64 s[0:1], s21, v0
	v_cvt_f32_u32_e32 v0, v0
	s_and_b64 s[0:1], vcc, s[0:1]
	v_fma_f32 v0, -v74, v0, v14
	v_cndmask_b32_e64 v104, v142, v0, s[0:1]
	v_add_u32_e32 v0, v49, v136
	v_cmp_gt_u32_e64 s[0:1], s21, v0
	v_cvt_f32_u32_e32 v0, v0
	s_and_b64 vcc, vcc, s[0:1]
	v_fma_f32 v0, -v74, v0, v15
	v_cndmask_b32_e32 v105, v142, v0, vcc
	v_max3_f32 v0, v48, v75, v76
	v_max3_f32 v0, v0, v77, v78
	v_max3_f32 v0, v0, v79, v80
	v_max3_f32 v0, v0, v92, v93
	v_max3_f32 v0, v0, v96, v97
	v_max3_f32 v0, v0, v100, v101
	v_max3_f32 v0, v0, v102, v103
	v_max3_f32 v64, v0, v104, v105
	v_max_i32_e32 v0, 0xffffffe0, v143
	v_add_u32_e32 v0, v0, v120
	v_mad_u64_u32 v[0:1], s[0:1], v0, s22, v[72:73]
	global_load_dwordx4 v[60:63], v[0:1], off offset:1024
	global_load_dwordx4 v[56:59], v[0:1], off offset:1056
	global_load_dwordx4 v[48:51], v[0:1], off offset:1088
	global_load_dwordx4 v[52:55], v[0:1], off offset:1120
	s_waitcnt vmcnt(7)
; #define MFMA32(a, b, c) __builtin_amdgcn_mfma_f32_32x32x16_bf16((a), (b), (c), 0, 0, 0)
; DI int crow(int r, int h) { return (r & 3) + 8 * (r >> 2) + 4 * h; }
; DI void swa_item(const Params& p, int item, int lane) {
;     ...
;   for (int t = 0; t < 5; ++t) {
;     const int kj0 = 32 * (w + t);
;     const int pos0 = (n - 1) * 128 + kj0;
;     if (t < 4) {
;       const int pn = pos0 + 32, pc = pn < 0 ? 0 : pn;
; #pragma unroll
;       for (int s = 0; s < 4; ++s) kn[s] = ldg8(kbase + (size_t)(pc + l31) * INC + 16 * s);
;     }
;     f32x16 acc;
; #pragma unroll
;     for (int r = 0; r < 16; ++r) acc[r] = 0.f;
; #pragma unroll
;     for (int s = 0; s < 4; ++s) acc = MFMA32(kc[s], qf[s], acc);
;     const bool tile_ok = pos0 >= 0;
; #pragma unroll
;     for (int r = 0; r < 16; ++r) {
;       int dist = 128 + qi - (kj0 + crow(r, h));
;       bool valid = tile_ok && (dist >= 0) && (dist < 128);
;       float v = valid ? acc[r] - slope * (float)dist : -INFINITY;
;       sc[t][r] = v;
;       m = fmaxf(m, v);
;     }
; #pragma unroll
;     for (int s = 0; s < 4; ++s) kc[s] = kn[s];
;   }
	v_mfma_f32_32x32x16_bf16 v[0:15], v[44:47], v[28:31], 0
	v_cmp_lt_i32_e32 vcc, -1, v143
	v_add_u32_e32 v45, 64, v98
	v_add_u32_e32 v144, v145, v45
	v_sub_u32_e32 v45, v117, v45
	v_add_u32_e32 v46, v45, v121
	s_waitcnt vmcnt(6)
	v_mfma_f32_32x32x16_bf16 v[0:15], v[40:43], v[24:27], v[0:15]
	s_waitcnt vmcnt(5)
	v_mfma_f32_32x32x16_bf16 v[0:15], v[32:35], v[16:19], v[0:15]
	v_sub_u32_e32 v32, v117, v65
	v_add_u32_e32 v33, v32, v121
	v_cmp_gt_u32_e64 s[0:1], s21, v33
	v_cvt_f32_i32_e32 v33, v33
	s_and_b64 s[0:1], vcc, s[0:1]
	s_waitcnt vmcnt(4)
	v_mfma_f32_32x32x16_bf16 v[0:15], v[36:39], v[20:23], v[0:15]
	s_nop 11
	v_fma_f32 v0, -v74, v33, v0
	v_cndmask_b32_e64 v106, v142, v0, s[0:1]
	v_add_u32_e32 v0, v32, v122
	v_cmp_gt_u32_e64 s[0:1], s21, v0
	v_cvt_f32_i32_e32 v0, v0
	s_and_b64 s[0:1], vcc, s[0:1]
	v_fma_f32 v0, -v74, v0, v1
	v_cndmask_b32_e64 v107, v142, v0, s[0:1]
	v_add_u32_e32 v0, v32, v123
	v_cmp_gt_u32_e64 s[0:1], s21, v0
	v_cvt_f32_i32_e32 v0, v0
	s_and_b64 s[0:1], vcc, s[0:1]
	v_fma_f32 v0, -v74, v0, v2
	v_cndmask_b32_e64 v108, v142, v0, s[0:1]
	v_add_u32_e32 v0, v32, v124
	v_cmp_gt_u32_e64 s[0:1], s21, v0
	v_cvt_f32_i32_e32 v0, v0
	s_and_b64 s[0:1], vcc, s[0:1]
	v_fma_f32 v0, -v74, v0, v3
	v_cndmask_b32_e64 v109, v142, v0, s[0:1]
	v_add_u32_e32 v0, v32, v125
	v_cmp_gt_u32_e64 s[0:1], s21, v0
	v_cvt_f32_i32_e32 v0, v0
	s_and_b64 s[0:1], vcc, s[0:1]
	v_fma_f32 v0, -v74, v0, v4
	v_cndmask_b32_e64 v110, v142, v0, s[0:1]
	v_add_u32_e32 v0, v32, v126
	v_cmp_gt_u32_e64 s[0:1], s21, v0
	v_cvt_f32_i32_e32 v0, v0
	s_and_b64 s[0:1], vcc, s[0:1]
	v_fma_f32 v0, -v74, v0, v5
	v_cndmask_b32_e64 v111, v142, v0, s[0:1]
	v_add_u32_e32 v0, v32, v127
	v_cmp_gt_u32_e64 s[0:1], s21, v0
	v_cvt_f32_i32_e32 v0, v0
	s_and_b64 s[0:1], vcc, s[0:1]
	v_fma_f32 v0, -v74, v0, v6
	v_cndmask_b32_e64 v112, v142, v0, s[0:1]
	v_add_u32_e32 v0, v32, v128
	v_cmp_gt_u32_e64 s[0:1], s21, v0
	v_cvt_f32_i32_e32 v0, v0
	s_and_b64 s[0:1], vcc, s[0:1]
	v_fma_f32 v0, -v74, v0, v7
	v_cndmask_b32_e64 v113, v142, v0, s[0:1]
	v_add_u32_e32 v0, v32, v129
	v_cmp_gt_u32_e64 s[0:1], s21, v0
	v_cvt_f32_i32_e32 v0, v0
	s_and_b64 s[0:1], vcc, s[0:1]
	v_fma_f32 v0, -v74, v0, v8
	v_cndmask_b32_e64 v114, v142, v0, s[0:1]
	v_add_u32_e32 v0, v32, v130
	v_cmp_gt_u32_e64 s[0:1], s21, v0
	v_cvt_f32_i32_e32 v0, v0
	s_and_b64 s[0:1], vcc, s[0:1]
	v_fma_f32 v0, -v74, v0, v9
	v_cndmask_b32_e64 v115, v142, v0, s[0:1]
	v_add_u32_e32 v0, v32, v131
	v_cmp_gt_u32_e64 s[0:1], s21, v0
	v_cvt_f32_i32_e32 v0, v0
	s_and_b64 s[0:1], vcc, s[0:1]
	v_fma_f32 v0, -v74, v0, v10
	v_cndmask_b32_e64 v116, v142, v0, s[0:1]
	v_add_u32_e32 v0, v32, v132
	v_cmp_gt_u32_e64 s[0:1], s21, v0
	v_cvt_f32_i32_e32 v0, v0
	s_and_b64 s[0:1], vcc, s[0:1]
	v_fma_f32 v0, -v74, v0, v11
	v_cndmask_b32_e64 v146, v142, v0, s[0:1]
	v_add_u32_e32 v0, v32, v133
	v_cmp_gt_u32_e64 s[0:1], s21, v0
	v_cvt_f32_i32_e32 v0, v0
	s_and_b64 s[0:1], vcc, s[0:1]
	v_fma_f32 v0, -v74, v0, v12
	v_cndmask_b32_e64 v147, v142, v0, s[0:1]
	v_add_u32_e32 v0, v32, v134
	v_cmp_gt_u32_e64 s[0:1], s21, v0
	v_cvt_f32_i32_e32 v0, v0
	s_and_b64 s[0:1], vcc, s[0:1]
	v_fma_f32 v0, -v74, v0, v13
	v_cndmask_b32_e64 v148, v142, v0, s[0:1]
	v_add_u32_e32 v0, v32, v135
	v_cmp_gt_u32_e64 s[0:1], s21, v0
	v_cvt_f32_i32_e32 v0, v0
	s_and_b64 s[0:1], vcc, s[0:1]
	v_fma_f32 v0, -v74, v0, v14
	v_cndmask_b32_e64 v149, v142, v0, s[0:1]
	v_add_u32_e32 v0, v32, v136
	v_cmp_gt_u32_e64 s[0:1], s21, v0
	v_cvt_f32_i32_e32 v0, v0
	s_and_b64 vcc, vcc, s[0:1]
	v_fma_f32 v0, -v74, v0, v15
	v_cndmask_b32_e32 v150, v142, v0, vcc
	v_max3_f32 v0, v64, v106, v107
	v_max3_f32 v0, v0, v108, v109
	v_max3_f32 v0, v0, v110, v111
	v_max3_f32 v0, v0, v112, v113
	v_max3_f32 v0, v0, v114, v115
	v_max3_f32 v0, v0, v116, v146
	v_max3_f32 v0, v0, v147, v148
	v_max3_f32 v44, v0, v149, v150
	v_max_i32_e32 v0, 0xffffffe0, v144
	v_add_u32_e32 v0, v0, v120
	v_mad_u64_u32 v[0:1], s[0:1], v0, s22, v[72:73]
	global_load_dwordx4 v[64:67], v[0:1], off offset:1024
	global_load_dwordx4 v[40:43], v[0:1], off offset:1056
	global_load_dwordx4 v[32:35], v[0:1], off offset:1088
	global_load_dwordx4 v[36:39], v[0:1], off offset:1120
	s_waitcnt vmcnt(7)
	v_mfma_f32_32x32x16_bf16 v[0:15], v[60:63], v[28:31], 0
	v_cmp_gt_u32_e64 s[0:1], s21, v46
	v_cvt_f32_i32_e32 v46, v46
	v_cmp_lt_i32_e32 vcc, -1, v144
	s_and_b64 s[0:1], vcc, s[0:1]
	v_add_u32_e32 v63, 0x60, v98
	v_add_u32_e32 v145, v145, v63
	v_sub_u32_e32 v63, v117, v63
	s_waitcnt vmcnt(6)
	v_mfma_f32_32x32x16_bf16 v[0:15], v[56:59], v[24:27], v[0:15]
	s_waitcnt vmcnt(5)
	v_mfma_f32_32x32x16_bf16 v[0:15], v[48:51], v[16:19], v[0:15]
	s_waitcnt vmcnt(4)
; #define MFMA32(a, b, c) __builtin_amdgcn_mfma_f32_32x32x16_bf16((a), (b), (c), 0, 0, 0)
; DI int crow(int r, int h) { return (r & 3) + 8 * (r >> 2) + 4 * h; }
; DI void swa_item(const Params& p, int item, int lane) {
;     ...
;   for (int t = 0; t < 5; ++t) {
;     const int kj0 = 32 * (w + t);
;     const int pos0 = (n - 1) * 128 + kj0;
;     if (t < 4) {
;       const int pn = pos0 + 32, pc = pn < 0 ? 0 : pn;
; #pragma unroll
;       for (int s = 0; s < 4; ++s) kn[s] = ldg8(kbase + (size_t)(pc + l31) * INC + 16 * s);
;     }
;     f32x16 acc;
; #pragma unroll
;     for (int r = 0; r < 16; ++r) acc[r] = 0.f;
; #pragma unroll
;     for (int s = 0; s < 4; ++s) acc = MFMA32(kc[s], qf[s], acc);
;     const bool tile_ok = pos0 >= 0;
; #pragma unroll
;     for (int r = 0; r < 16; ++r) {
;       int dist = 128 + qi - (kj0 + crow(r, h));
;       bool valid = tile_ok && (dist >= 0) && (dist < 128);
;       float v = valid ? acc[r] - slope * (float)dist : -INFINITY;
;       sc[t][r] = v;
;       m = fmaxf(m, v);
;     }
; #pragma unroll
;     for (int s = 0; s < 4; ++s) kc[s] = kn[s];
;   }
	v_mfma_f32_32x32x16_bf16 v[0:15], v[52:55], v[20:23], v[0:15]
	s_nop 11
	v_fma_f32 v0, -v74, v46, v0
	v_cndmask_b32_e64 v60, v142, v0, s[0:1]
	v_add_u32_e32 v0, v45, v122
	v_cmp_gt_u32_e64 s[0:1], s21, v0
	v_cvt_f32_i32_e32 v0, v0
	s_and_b64 s[0:1], vcc, s[0:1]
	v_fma_f32 v0, -v74, v0, v1
	v_cndmask_b32_e64 v61, v142, v0, s[0:1]
	v_add_u32_e32 v0, v45, v123
	v_cmp_gt_u32_e64 s[0:1], s21, v0
	v_cvt_f32_i32_e32 v0, v0
	s_and_b64 s[0:1], vcc, s[0:1]
	v_fma_f32 v0, -v74, v0, v2
	v_cndmask_b32_e64 v151, v142, v0, s[0:1]
	v_add_u32_e32 v0, v45, v124
	v_cmp_gt_u32_e64 s[0:1], s21, v0
	v_cvt_f32_i32_e32 v0, v0
	s_and_b64 s[0:1], vcc, s[0:1]
	v_fma_f32 v0, -v74, v0, v3
	v_cndmask_b32_e64 v152, v142, v0, s[0:1]
	v_add_u32_e32 v0, v45, v125
	v_cmp_gt_u32_e64 s[0:1], s21, v0
	v_cvt_f32_i32_e32 v0, v0
	s_and_b64 s[0:1], vcc, s[0:1]
	v_fma_f32 v0, -v74, v0, v4
	v_cndmask_b32_e64 v153, v142, v0, s[0:1]
	v_add_u32_e32 v0, v45, v126
	v_cmp_gt_u32_e64 s[0:1], s21, v0
	v_cvt_f32_i32_e32 v0, v0
	s_and_b64 s[0:1], vcc, s[0:1]
	v_fma_f32 v0, -v74, v0, v5
	v_cndmask_b32_e64 v154, v142, v0, s[0:1]
	v_add_u32_e32 v0, v45, v127
	v_cmp_gt_u32_e64 s[0:1], s21, v0
	v_cvt_f32_i32_e32 v0, v0
	s_and_b64 s[0:1], vcc, s[0:1]
	v_fma_f32 v0, -v74, v0, v6
	v_cndmask_b32_e64 v155, v142, v0, s[0:1]
	v_add_u32_e32 v0, v45, v128
	v_cmp_gt_u32_e64 s[0:1], s21, v0
	v_cvt_f32_i32_e32 v0, v0
	s_and_b64 s[0:1], vcc, s[0:1]
	v_fma_f32 v0, -v74, v0, v7
	v_cndmask_b32_e64 v156, v142, v0, s[0:1]
	v_add_u32_e32 v0, v45, v129
	v_cmp_gt_u32_e64 s[0:1], s21, v0
	v_cvt_f32_i32_e32 v0, v0
	s_and_b64 s[0:1], vcc, s[0:1]
	v_fma_f32 v0, -v74, v0, v8
	v_cndmask_b32_e64 v157, v142, v0, s[0:1]
	v_add_u32_e32 v0, v45, v130
	v_cmp_gt_u32_e64 s[0:1], s21, v0
	v_cvt_f32_i32_e32 v0, v0
	s_and_b64 s[0:1], vcc, s[0:1]
	v_fma_f32 v0, -v74, v0, v9
	v_cndmask_b32_e64 v158, v142, v0, s[0:1]
	v_add_u32_e32 v0, v45, v131
	v_cmp_gt_u32_e64 s[0:1], s21, v0
	v_cvt_f32_i32_e32 v0, v0
	s_and_b64 s[0:1], vcc, s[0:1]
	v_fma_f32 v0, -v74, v0, v10
	v_cndmask_b32_e64 v159, v142, v0, s[0:1]
	v_add_u32_e32 v0, v45, v132
	v_cmp_gt_u32_e64 s[0:1], s21, v0
	v_cvt_f32_i32_e32 v0, v0
	s_and_b64 s[0:1], vcc, s[0:1]
	v_fma_f32 v0, -v74, v0, v11
	v_cndmask_b32_e64 v160, v142, v0, s[0:1]
	v_add_u32_e32 v0, v45, v133
	v_cmp_gt_u32_e64 s[0:1], s21, v0
	v_cvt_f32_i32_e32 v0, v0
	s_and_b64 s[0:1], vcc, s[0:1]
	v_fma_f32 v0, -v74, v0, v12
	v_cndmask_b32_e64 v161, v142, v0, s[0:1]
	v_add_u32_e32 v0, v45, v134
	v_cmp_gt_u32_e64 s[0:1], s21, v0
	v_cvt_f32_i32_e32 v0, v0
	s_and_b64 s[0:1], vcc, s[0:1]
	v_fma_f32 v0, -v74, v0, v13
	v_cndmask_b32_e64 v162, v142, v0, s[0:1]
	v_add_u32_e32 v0, v45, v135
	v_cmp_gt_u32_e64 s[0:1], s21, v0
	v_cvt_f32_i32_e32 v0, v0
	s_and_b64 s[0:1], vcc, s[0:1]
	v_fma_f32 v0, -v74, v0, v14
	v_cndmask_b32_e64 v163, v142, v0, s[0:1]
	v_add_u32_e32 v0, v45, v136
	v_cmp_gt_u32_e64 s[0:1], s21, v0
	v_cvt_f32_i32_e32 v0, v0
	s_and_b64 vcc, vcc, s[0:1]
	v_fma_f32 v0, -v74, v0, v15
	v_cndmask_b32_e32 v164, v142, v0, vcc
	v_max3_f32 v0, v44, v60, v61
	v_max3_f32 v0, v0, v151, v152
	v_max3_f32 v0, v0, v153, v154
	v_max3_f32 v0, v0, v155, v156
	v_max3_f32 v0, v0, v157, v158
	v_max3_f32 v0, v0, v159, v160
	v_max3_f32 v0, v0, v161, v162
	v_max3_f32 v62, v0, v163, v164
	v_add_u32_e32 v0, v145, v120
	v_mad_u64_u32 v[0:1], s[0:1], v0, s22, v[72:73]
	global_load_dwordx4 v[56:59], v[0:1], off offset:1024
	global_load_dwordx4 v[52:55], v[0:1], off offset:1056
	global_load_dwordx4 v[44:47], v[0:1], off offset:1088
	global_load_dwordx4 v[48:51], v[0:1], off offset:1120
	s_waitcnt vmcnt(7)
	v_mfma_f32_32x32x16_bf16 v[0:15], v[64:67], v[28:31], 0
	v_cmp_lt_i32_e32 vcc, -1, v145
	s_waitcnt vmcnt(6)
	v_mfma_f32_32x32x16_bf16 v[0:15], v[40:43], v[24:27], v[0:15]
	s_waitcnt vmcnt(5)
	v_mfma_f32_32x32x16_bf16 v[0:15], v[32:35], v[16:19], v[0:15]
	v_add_u32_e32 v33, v63, v121
	v_cmp_gt_u32_e64 s[0:1], s21, v33
	v_cvt_f32_i32_e32 v33, v33
	s_and_b64 s[0:1], vcc, s[0:1]
	v_add_u32_e32 v32, 0x80, v89
	s_waitcnt vmcnt(4)
	v_mfma_f32_32x32x16_bf16 v[0:15], v[36:39], v[20:23], v[0:15]
	s_nop 11
	v_fma_f32 v0, -v74, v33, v0
	v_cndmask_b32_e64 v33, v142, v0, s[0:1]
	v_add_u32_e32 v0, v63, v122
	v_cmp_gt_u32_e64 s[0:1], s21, v0
	v_cvt_f32_i32_e32 v0, v0
	s_and_b64 s[0:1], vcc, s[0:1]
	v_fma_f32 v0, -v74, v0, v1
	v_add_u32_e32 v1, v63, v123
	v_cndmask_b32_e64 v34, v142, v0, s[0:1]
	v_cmp_gt_u32_e64 s[0:1], s21, v1
	v_cvt_f32_i32_e32 v1, v1
	s_and_b64 s[0:1], vcc, s[0:1]
	v_max3_f32 v0, v62, v33, v34
	v_fma_f32 v1, -v74, v1, v2
	v_cndmask_b32_e64 v35, v142, v1, s[0:1]
	v_add_u32_e32 v1, v63, v124
	v_cmp_gt_u32_e64 s[0:1], s21, v1
	v_cvt_f32_i32_e32 v1, v1
	s_and_b64 s[0:1], vcc, s[0:1]
	v_fma_f32 v1, -v74, v1, v3
	v_cndmask_b32_e64 v36, v142, v1, s[0:1]
	v_add_u32_e32 v1, v63, v125
	v_cmp_gt_u32_e64 s[0:1], s21, v1
	v_cvt_f32_i32_e32 v1, v1
	s_and_b64 s[0:1], vcc, s[0:1]
	v_max3_f32 v0, v0, v35, v36
	v_fma_f32 v1, -v74, v1, v4
	v_cndmask_b32_e64 v37, v142, v1, s[0:1]
	v_add_u32_e32 v1, v63, v126
	v_cmp_gt_u32_e64 s[0:1], s21, v1
	v_cvt_f32_i32_e32 v1, v1
	s_and_b64 s[0:1], vcc, s[0:1]
	v_fma_f32 v1, -v74, v1, v5
	v_cndmask_b32_e64 v38, v142, v1, s[0:1]
	v_add_u32_e32 v1, v63, v127
	v_cmp_gt_u32_e64 s[0:1], s21, v1
	v_cvt_f32_i32_e32 v1, v1
	s_and_b64 s[0:1], vcc, s[0:1]
	v_max3_f32 v0, v0, v37, v38
	v_fma_f32 v1, -v74, v1, v6
	v_cndmask_b32_e64 v39, v142, v1, s[0:1]
	v_add_u32_e32 v1, v63, v128
	v_cmp_gt_u32_e64 s[0:1], s21, v1
	v_cvt_f32_i32_e32 v1, v1
	s_and_b64 s[0:1], vcc, s[0:1]
	v_fma_f32 v1, -v74, v1, v7
	v_cndmask_b32_e64 v40, v142, v1, s[0:1]
	v_add_u32_e32 v1, v63, v129
	v_cmp_gt_u32_e64 s[0:1], s21, v1
	v_cvt_f32_i32_e32 v1, v1
; DI int crow(int r, int h) { return (r & 3) + 8 * (r >> 2) + 4 * h; }
; DI float xor32_add(float x) { auto r = __builtin_amdgcn_permlane32_swap(__float_as_uint(x), __float_as_uint(x), false, false); return __uint_as_float(r[0]) + __uint_as_float(r[1]); }
; DI float xor32_max(float x) { auto r = __builtin_amdgcn_permlane32_swap(__float_as_uint(x), __float_as_uint(x), false, false); return fmaxf(__uint_as_float(r[0]), __uint_as_float(r[1])); }
; DI float ex2(float x) { return __builtin_amdgcn_exp2f(x); }
; DI void swa_item(const Params& p, int item, int lane) {
;     ...
;     const bool tile_ok = pos0 >= 0;
; #pragma unroll
;     for (int r = 0; r < 16; ++r) {
;       int dist = 128 + qi - (kj0 + crow(r, h));
;       bool valid = tile_ok && (dist >= 0) && (dist < 128);
;       float v = valid ? acc[r] - slope * (float)dist : -INFINITY;
;       sc[t][r] = v;
;       m = fmaxf(m, v);
;     }
; #pragma unroll
;     for (int s = 0; s < 4; ++s) kc[s] = kn[s];
;   }
;   m = xor32_max(m);
;   float sum = 0.f;
; #pragma unroll
;   for (int t = 0; t < 5; ++t)
; #pragma unroll
;     for (int r = 0; r < 16; ++r) { float e = ex2(sc[t][r] - m); sc[t][r] = e; sum += e; }
;   sum = xor32_add(sum);
	s_and_b64 s[0:1], vcc, s[0:1]
	v_max3_f32 v0, v0, v39, v40
	v_fma_f32 v1, -v74, v1, v8
	v_cndmask_b32_e64 v41, v142, v1, s[0:1]
	v_add_u32_e32 v1, v63, v130
	v_cmp_gt_u32_e64 s[0:1], s21, v1
	v_cvt_f32_i32_e32 v1, v1
	s_and_b64 s[0:1], vcc, s[0:1]
	v_fma_f32 v1, -v74, v1, v9
	v_cndmask_b32_e64 v42, v142, v1, s[0:1]
	v_add_u32_e32 v1, v63, v131
	v_cmp_gt_u32_e64 s[0:1], s21, v1
	v_cvt_f32_i32_e32 v1, v1
	s_and_b64 s[0:1], vcc, s[0:1]
	v_max3_f32 v0, v0, v41, v42
	v_fma_f32 v1, -v74, v1, v10
	v_cndmask_b32_e64 v43, v142, v1, s[0:1]
	v_add_u32_e32 v1, v63, v132
	v_cmp_gt_u32_e64 s[0:1], s21, v1
	v_cvt_f32_i32_e32 v1, v1
	s_and_b64 s[0:1], vcc, s[0:1]
	v_fma_f32 v1, -v74, v1, v11
	v_cndmask_b32_e64 v65, v142, v1, s[0:1]
	v_add_u32_e32 v1, v63, v133
	v_cmp_gt_u32_e64 s[0:1], s21, v1
	v_cvt_f32_i32_e32 v1, v1
	s_and_b64 s[0:1], vcc, s[0:1]
	v_max3_f32 v0, v0, v43, v65
	v_fma_f32 v1, -v74, v1, v12
	v_cndmask_b32_e64 v72, v142, v1, s[0:1]
	v_add_u32_e32 v1, v63, v134
	v_cmp_gt_u32_e64 s[0:1], s21, v1
	v_cvt_f32_i32_e32 v1, v1
	s_and_b64 s[0:1], vcc, s[0:1]
	v_fma_f32 v1, -v74, v1, v13
	v_cndmask_b32_e64 v73, v142, v1, s[0:1]
	v_add_u32_e32 v1, v63, v135
	v_cmp_gt_u32_e64 s[0:1], s21, v1
	v_cvt_f32_i32_e32 v1, v1
	s_and_b64 s[0:1], vcc, s[0:1]
	v_max3_f32 v0, v0, v72, v73
	v_fma_f32 v1, -v74, v1, v14
	v_cndmask_b32_e64 v166, v142, v1, s[0:1]
	v_add_u32_e32 v1, v63, v136
	v_cmp_gt_u32_e64 s[0:1], s21, v1
	v_cvt_f32_i32_e32 v1, v1
	s_and_b64 vcc, vcc, s[0:1]
	s_mov_b32 s0, 0x3fb8aa3b
	v_fma_f32 v1, -v74, v1, v15
	v_cndmask_b32_e32 v165, v142, v1, vcc
	v_max3_f32 v62, v0, v166, v165
	s_waitcnt vmcnt(3)
	v_mfma_f32_32x32x16_bf16 v[0:15], v[56:59], v[28:31], 0
	v_sub_u32_e32 v31, v99, v98
	s_waitcnt vmcnt(2)
	v_mfma_f32_32x32x16_bf16 v[0:15], v[52:55], v[24:27], v[0:15]
	s_waitcnt vmcnt(1)
	v_mfma_f32_32x32x16_bf16 v[0:15], v[44:47], v[16:19], v[0:15]
	v_add_u32_e32 v16, v31, v121
	v_cmp_gt_u32_e32 vcc, s21, v16
	v_cvt_f32_i32_e32 v16, v16
	s_waitcnt vmcnt(0)
	v_mfma_f32_32x32x16_bf16 v[0:15], v[48:51], v[20:23], v[0:15]
	s_nop 11
	v_fma_f32 v0, -v74, v16, v0
	v_cndmask_b32_e32 v16, v142, v0, vcc
	v_add_u32_e32 v0, v31, v122
	v_cmp_gt_u32_e32 vcc, s21, v0
	v_cvt_f32_i32_e32 v0, v0
	v_fma_f32 v0, -v74, v0, v1
	v_cndmask_b32_e32 v17, v142, v0, vcc
	v_add_u32_e32 v0, v31, v123
	v_cmp_gt_u32_e32 vcc, s21, v0
	v_cvt_f32_i32_e32 v0, v0
	v_fma_f32 v0, -v74, v0, v2
	v_cndmask_b32_e32 v18, v142, v0, vcc
	v_add_u32_e32 v0, v31, v124
	v_cmp_gt_u32_e32 vcc, s21, v0
	v_cvt_f32_i32_e32 v0, v0
	v_fma_f32 v0, -v74, v0, v3
	v_cndmask_b32_e32 v19, v142, v0, vcc
	v_add_u32_e32 v0, v31, v125
	v_cmp_gt_u32_e32 vcc, s21, v0
	v_cvt_f32_i32_e32 v0, v0
	v_fma_f32 v0, -v74, v0, v4
	v_cndmask_b32_e32 v20, v142, v0, vcc
	v_add_u32_e32 v0, v31, v126
	v_cmp_gt_u32_e32 vcc, s21, v0
	v_cvt_f32_i32_e32 v0, v0
	v_fma_f32 v0, -v74, v0, v5
	v_cndmask_b32_e32 v21, v142, v0, vcc
	v_add_u32_e32 v0, v31, v127
	v_cmp_gt_u32_e32 vcc, s21, v0
	v_cvt_f32_i32_e32 v0, v0
	v_fma_f32 v0, -v74, v0, v6
	v_cndmask_b32_e32 v22, v142, v0, vcc
	v_add_u32_e32 v0, v31, v128
	v_cmp_gt_u32_e32 vcc, s21, v0
	v_cvt_f32_i32_e32 v0, v0
	v_fma_f32 v0, -v74, v0, v7
	v_cndmask_b32_e32 v23, v142, v0, vcc
	v_add_u32_e32 v0, v31, v129
	v_cmp_gt_u32_e32 vcc, s21, v0
	v_cvt_f32_i32_e32 v0, v0
	v_fma_f32 v0, -v74, v0, v8
	v_cndmask_b32_e32 v24, v142, v0, vcc
	v_add_u32_e32 v0, v31, v130
	v_cmp_gt_u32_e32 vcc, s21, v0
	v_cvt_f32_i32_e32 v0, v0
	v_fma_f32 v0, -v74, v0, v9
	v_cndmask_b32_e32 v25, v142, v0, vcc
	v_add_u32_e32 v0, v31, v131
	v_cmp_gt_u32_e32 vcc, s21, v0
	v_cvt_f32_i32_e32 v0, v0
	v_fma_f32 v0, -v74, v0, v10
	v_cndmask_b32_e32 v26, v142, v0, vcc
	v_add_u32_e32 v0, v31, v132
	v_cmp_gt_u32_e32 vcc, s21, v0
	v_cvt_f32_i32_e32 v0, v0
	v_fma_f32 v0, -v74, v0, v11
	v_cndmask_b32_e32 v27, v142, v0, vcc
	v_add_u32_e32 v0, v31, v133
	v_cmp_gt_u32_e32 vcc, s21, v0
	v_cvt_f32_i32_e32 v0, v0
	v_fma_f32 v0, -v74, v0, v12
	v_cndmask_b32_e32 v28, v142, v0, vcc
	v_add_u32_e32 v0, v31, v134
	v_cmp_gt_u32_e32 vcc, s21, v0
	v_cvt_f32_i32_e32 v0, v0
	v_fma_f32 v0, -v74, v0, v13
	v_cndmask_b32_e32 v29, v142, v0, vcc
	v_add_u32_e32 v0, v31, v135
	v_cmp_gt_u32_e32 vcc, s21, v0
	v_cvt_f32_i32_e32 v0, v0
	v_fma_f32 v0, -v74, v0, v14
	v_cndmask_b32_e32 v30, v142, v0, vcc
	v_add_u32_e32 v0, v31, v136
	v_cmp_gt_u32_e32 vcc, s21, v0
	v_cvt_f32_i32_e32 v0, v0
	v_fma_f32 v0, -v74, v0, v15
	v_cndmask_b32_e32 v31, v142, v0, vcc
	v_max3_f32 v0, v62, v16, v17
	v_max3_f32 v0, v0, v18, v19
	v_max3_f32 v0, v0, v20, v21
	v_max3_f32 v0, v0, v22, v23
	v_max3_f32 v0, v0, v24, v25
	v_max3_f32 v0, v0, v26, v27
	v_max3_f32 v0, v0, v28, v29
	v_max3_f32 v0, v0, v30, v31
	v_mov_b32_e32 v1, v0
	s_nop 1
	v_permlane32_swap_b32_e32 v0, v1
	v_max_f32_e32 v1, v1, v1
	v_max_f32_e32 v0, v0, v0
	v_max_f32_e32 v50, v0, v1
	v_sub_f32_e32 v0, v75, v50
	v_exp_f32_e32 v0, v0
	v_sub_f32_e32 v1, v76, v50
	v_exp_f32_e32 v1, v1
	v_sub_f32_e32 v45, v106, v50
	v_add_f32_e32 v2, 0, v0
	v_sub_f32_e32 v33, v33, v50
	v_add_f32_e32 v3, v1, v2
	v_sub_f32_e32 v2, v77, v50
	v_exp_f32_e32 v2, v2
	v_exp_f32_e32 v52, v33
	v_sub_f32_e32 v34, v34, v50
	v_exp_f32_e32 v53, v34
	v_add_f32_e32 v4, v2, v3
	v_sub_f32_e32 v3, v78, v50
	v_exp_f32_e32 v3, v3
	v_sub_f32_e32 v34, v35, v50
	v_exp_f32_e32 v54, v34
	v_sub_f32_e32 v34, v36, v50
	v_add_f32_e32 v5, v3, v4
	v_sub_f32_e32 v4, v79, v50
	v_exp_f32_e32 v4, v4
	v_exp_f32_e32 v55, v34
	v_sub_f32_e32 v34, v37, v50
	v_exp_f32_e32 v56, v34
	v_add_f32_e32 v6, v4, v5
	v_sub_f32_e32 v5, v80, v50
	v_exp_f32_e32 v5, v5
	v_sub_f32_e32 v34, v38, v50
	v_exp_f32_e32 v57, v34
	v_sub_f32_e32 v34, v39, v50
	v_add_f32_e32 v7, v5, v6
	v_sub_f32_e32 v6, v92, v50
; DI float xor32_add(float x) { auto r = __builtin_amdgcn_permlane32_swap(__float_as_uint(x), __float_as_uint(x), false, false); return __uint_as_float(r[0]) + __uint_as_float(r[1]); }
; DI float xor32_max(float x) { auto r = __builtin_amdgcn_permlane32_swap(__float_as_uint(x), __float_as_uint(x), false, false); return fmaxf(__uint_as_float(r[0]), __uint_as_float(r[1])); }
; DI float ex2(float x) { return __builtin_amdgcn_exp2f(x); }
; DI void swa_item(const Params& p, int item, int lane) {
;     ...
;   m = xor32_max(m);
;   float sum = 0.f;
; #pragma unroll
;   for (int t = 0; t < 5; ++t)
; #pragma unroll
;     for (int r = 0; r < 16; ++r) { float e = ex2(sc[t][r] - m); sc[t][r] = e; sum += e; }
;   sum = xor32_add(sum);
	v_exp_f32_e32 v6, v6
	v_exp_f32_e32 v58, v34
	v_sub_f32_e32 v34, v40, v50
	v_exp_f32_e32 v59, v34
	v_add_f32_e32 v8, v6, v7
	v_sub_f32_e32 v7, v93, v50
	v_exp_f32_e32 v7, v7
	v_sub_f32_e32 v34, v41, v50
	v_sub_f32_e32 v16, v16, v50
	v_sub_f32_e32 v17, v17, v50
	v_add_f32_e32 v9, v7, v8
	v_sub_f32_e32 v8, v96, v50
	v_exp_f32_e32 v8, v8
	v_exp_f32_e32 v96, v45
	v_sub_f32_e32 v45, v107, v50
	v_exp_f32_e32 v35, v17
	v_add_f32_e32 v10, v8, v9
	v_sub_f32_e32 v9, v97, v50
	v_exp_f32_e32 v9, v9
	v_exp_f32_e32 v97, v45
	v_sub_f32_e32 v45, v108, v50
	v_sub_f32_e32 v17, v18, v50
	v_add_f32_e32 v11, v9, v10
	v_sub_f32_e32 v10, v100, v50
	v_exp_f32_e32 v10, v10
	v_exp_f32_e32 v100, v45
	v_sub_f32_e32 v45, v109, v50
	v_exp_f32_e32 v36, v17
	v_add_f32_e32 v12, v10, v11
	v_sub_f32_e32 v11, v101, v50
	v_exp_f32_e32 v11, v11
	v_exp_f32_e32 v101, v45
	v_sub_f32_e32 v45, v110, v50
	v_sub_f32_e32 v17, v19, v50
	v_add_f32_e32 v13, v11, v12
	v_sub_f32_e32 v12, v102, v50
	v_exp_f32_e32 v12, v12
	v_exp_f32_e32 v37, v17
	v_sub_f32_e32 v17, v20, v50
	v_exp_f32_e32 v38, v17
	v_add_f32_e32 v14, v12, v13
	v_sub_f32_e32 v13, v103, v50
	v_exp_f32_e32 v13, v13
	v_sub_f32_e32 v17, v21, v50
	v_exp_f32_e32 v39, v17
	v_sub_f32_e32 v17, v22, v50
	v_add_f32_e32 v15, v13, v14
	v_sub_f32_e32 v14, v104, v50
	v_exp_f32_e32 v14, v14
	v_exp_f32_e32 v104, v45
	v_sub_f32_e32 v45, v111, v50
	v_exp_f32_e32 v40, v17
	v_add_f32_e32 v44, v14, v15
	v_sub_f32_e32 v15, v105, v50
	v_exp_f32_e32 v15, v15
	v_exp_f32_e32 v105, v45
	v_sub_f32_e32 v45, v112, v50
	v_exp_f32_e32 v108, v45
	v_add_f32_e32 v44, v15, v44
	v_add_f32_e32 v44, v96, v44
	v_add_f32_e32 v44, v97, v44
	v_add_f32_e32 v44, v100, v44
	v_sub_f32_e32 v45, v113, v50
	v_add_f32_e32 v44, v101, v44
	v_exp_f32_e32 v109, v45
	v_sub_f32_e32 v45, v114, v50
	v_add_f32_e32 v44, v104, v44
	v_exp_f32_e32 v110, v45
	v_sub_f32_e32 v45, v115, v50
	v_add_f32_e32 v44, v105, v44
	v_exp_f32_e32 v111, v45
	v_sub_f32_e32 v45, v116, v50
	v_add_f32_e32 v44, v108, v44
	v_exp_f32_e32 v112, v45
	v_sub_f32_e32 v45, v146, v50
	v_add_f32_e32 v44, v109, v44
	v_exp_f32_e32 v113, v45
	v_sub_f32_e32 v45, v147, v50
	v_add_f32_e32 v44, v110, v44
	v_exp_f32_e32 v114, v45
	v_sub_f32_e32 v45, v148, v50
	v_add_f32_e32 v44, v111, v44
	v_exp_f32_e32 v115, v45
	v_sub_f32_e32 v45, v149, v50
	v_add_f32_e32 v44, v112, v44
	v_exp_f32_e32 v116, v45
	v_sub_f32_e32 v45, v150, v50
	v_add_f32_e32 v44, v113, v44
	v_exp_f32_e32 v117, v45
	v_sub_f32_e32 v45, v60, v50
	v_add_f32_e32 v44, v114, v44
	v_exp_f32_e32 v62, v45
	v_sub_f32_e32 v45, v61, v50
	v_add_f32_e32 v44, v115, v44
	v_exp_f32_e32 v63, v45
	v_sub_f32_e32 v45, v151, v50
	v_add_f32_e32 v44, v116, v44
	v_exp_f32_e32 v66, v45
	v_sub_f32_e32 v45, v152, v50
	v_add_f32_e32 v44, v117, v44
	v_exp_f32_e32 v67, v45
	v_sub_f32_e32 v45, v153, v50
	v_add_f32_e32 v44, v62, v44
	v_exp_f32_e32 v74, v45
	v_sub_f32_e32 v45, v154, v50
	v_add_f32_e32 v44, v63, v44
	v_exp_f32_e32 v75, v45
	v_sub_f32_e32 v45, v155, v50
	v_add_f32_e32 v44, v66, v44
	v_exp_f32_e32 v78, v45
	v_sub_f32_e32 v45, v156, v50
	v_add_f32_e32 v44, v67, v44
	v_exp_f32_e32 v79, v45
	v_sub_f32_e32 v45, v157, v50
	v_add_f32_e32 v44, v74, v44
	v_exp_f32_e32 v92, v45
	v_sub_f32_e32 v45, v158, v50
	v_add_f32_e32 v44, v75, v44
	v_exp_f32_e32 v93, v45
	v_sub_f32_e32 v45, v159, v50
	v_add_f32_e32 v44, v78, v44
	v_exp_f32_e32 v98, v45
	v_sub_f32_e32 v45, v160, v50
	v_add_f32_e32 v44, v79, v44
	v_exp_f32_e32 v99, v45
	v_sub_f32_e32 v45, v161, v50
	v_add_f32_e32 v44, v92, v44
	v_exp_f32_e32 v102, v45
	v_sub_f32_e32 v45, v162, v50
	v_add_f32_e32 v44, v93, v44
	v_exp_f32_e32 v103, v45
	v_sub_f32_e32 v45, v163, v50
	v_add_f32_e32 v44, v98, v44
	v_exp_f32_e32 v106, v45
	v_sub_f32_e32 v45, v164, v50
	v_add_f32_e32 v44, v99, v44
	v_exp_f32_e32 v107, v45
	v_add_f32_e32 v44, v102, v44
	v_add_f32_e32 v44, v103, v44
	v_add_f32_e32 v44, v106, v44
	v_add_f32_e32 v44, v107, v44
	v_add_f32_e32 v33, v52, v44
	v_add_f32_e32 v33, v53, v33
	v_add_f32_e32 v33, v54, v33
	v_add_f32_e32 v33, v55, v33
	v_add_f32_e32 v33, v56, v33
	v_exp_f32_e32 v60, v34
	v_sub_f32_e32 v34, v42, v50
	v_add_f32_e32 v33, v57, v33
	v_exp_f32_e32 v61, v34
	v_sub_f32_e32 v34, v43, v50
	v_add_f32_e32 v33, v58, v33
	v_exp_f32_e32 v64, v34
	v_sub_f32_e32 v34, v65, v50
	v_add_f32_e32 v33, v59, v33
	v_exp_f32_e32 v65, v34
	v_sub_f32_e32 v34, v72, v50
	v_add_f32_e32 v33, v60, v33
	v_exp_f32_e32 v72, v34
	v_sub_f32_e32 v34, v73, v50
	v_add_f32_e32 v33, v61, v33
	v_exp_f32_e32 v73, v34
	v_sub_f32_e32 v34, v166, v50
	v_add_f32_e32 v33, v64, v33
	v_exp_f32_e32 v76, v34
	v_sub_f32_e32 v34, v165, v50
	v_add_f32_e32 v33, v65, v33
	v_exp_f32_e32 v77, v34
	v_add_f32_e32 v33, v72, v33
	v_exp_f32_e32 v34, v16
	v_add_f32_e32 v33, v73, v33
	v_add_f32_e32 v33, v76, v33
	v_add_f32_e32 v33, v77, v33
	v_add_f32_e32 v16, v34, v33
	v_add_f32_e32 v16, v35, v16
	v_add_f32_e32 v16, v36, v16
	v_sub_f32_e32 v17, v23, v50
	v_add_f32_e32 v16, v37, v16
	v_exp_f32_e32 v41, v17
	v_sub_f32_e32 v17, v24, v50
	v_add_f32_e32 v16, v38, v16
	v_exp_f32_e32 v42, v17
	v_sub_f32_e32 v17, v25, v50
	v_add_f32_e32 v16, v39, v16
	v_exp_f32_e32 v43, v17
	v_sub_f32_e32 v17, v26, v50
	v_add_f32_e32 v16, v40, v16
	v_exp_f32_e32 v44, v17
	v_sub_f32_e32 v17, v27, v50
	v_add_f32_e32 v16, v41, v16
	v_exp_f32_e32 v45, v17
	v_sub_f32_e32 v17, v28, v50
	v_add_f32_e32 v16, v42, v16
	v_exp_f32_e32 v46, v17
	v_sub_f32_e32 v17, v29, v50
	v_add_f32_e32 v16, v43, v16
	v_exp_f32_e32 v47, v17
	v_sub_f32_e32 v17, v30, v50
	v_add_f32_e32 v16, v44, v16
	v_exp_f32_e32 v48, v17
	v_sub_f32_e32 v17, v31, v50
	v_add_f32_e32 v16, v45, v16
	v_exp_f32_e32 v49, v17
	v_add_f32_e32 v16, v46, v16
; #define MFMA32(a, b, c) __builtin_amdgcn_mfma_f32_32x32x16_bf16((a), (b), (c), 0, 0, 0)
; DI float xor32_add(float x) { auto r = __builtin_amdgcn_permlane32_swap(__float_as_uint(x), __float_as_uint(x), false, false); return __uint_as_float(r[0]) + __uint_as_float(r[1]); }
; DI float ex2(float x) { return __builtin_amdgcn_exp2f(x); }
; DI void swa_item(const Params& p, int item, int lane) {
;     ...
;   sum = xor32_add(sum);
;   const float inv = 1.f / (sum + ex2(sink - m));
;   f32x16 oacc[2];
; #pragma unroll
;   for (int dt = 0; dt < 2; ++dt)
; #pragma unroll
;     for (int r = 0; r < 16; ++r) oacc[dt][r] = 0.f;
;   const bf16_t* vbase = vat + ((size_t)(b * 2 + g) * 64 + l31) * SEQ + 8 * h;
; #pragma unroll
;   for (int t = 0; t < 5; ++t) {
;     const int pos0 = (n - 1) * 128 + 32 * (w + t), pc = pos0 < 0 ? 0 : pos0;
; #pragma unroll
;     for (int r = 0; r < 16; ++r) sc[t][r] *= inv;
; #pragma unroll
;     for (int s2 = 0; s2 < 2; ++s2) {
;       bf16x8 pb = packp(sc[t], s2);
; #pragma unroll
;       for (int dt = 0; dt < 2; ++dt)
;         oacc[dt] = MFMA32(ldg8(vbase + (size_t)(32 * dt) * SEQ + pc + 16 * s2), pb, oacc[dt]);
;     }
;   }
	v_add_f32_e32 v16, v47, v16
	v_add_f32_e32 v16, v48, v16
	v_add_f32_e32 v16, v49, v16
	v_mov_b32_e32 v17, v16
	s_nop 1
	v_permlane32_swap_b32_e32 v16, v17
	v_add_f32_e32 v16, v16, v17
	v_fma_f32 v17, v95, s0, -v50
	v_exp_f32_e32 v17, v17
	v_max_i32_e32 v33, 0, v143
	v_add_f32_e32 v16, v16, v17
	v_div_scale_f32 v17, s[0:1], v16, v16, 1.0
	v_rcp_f32_e32 v18, v17
	s_nop 0
	v_fma_f32 v19, -v17, v18, 1.0
	v_fmac_f32_e32 v18, v19, v18
	v_div_scale_f32 v19, vcc, 1.0, v16, 1.0
	v_mul_f32_e32 v20, v19, v18
	v_fma_f32 v21, -v17, v20, v19
	v_fmac_f32_e32 v20, v21, v18
	v_fma_f32 v17, -v17, v20, v19
	v_div_fmas_f32 v17, v17, v18, v20
	v_div_fixup_f32 v50, v17, v16, 1.0
	v_lshlrev_b32_e32 v16, 7, v91
	v_or3_b32 v16, v94, v16, v119
	v_lshlrev_b32_e32 v80, 13, v16
	v_pk_mul_f32 v[146:147], v[8:9], v[50:51] op_sel_hi:[1,0]
	v_max_i32_e32 v8, 0, v89
	v_lshl_add_u64 v[94:95], v[80:81], 1, v[84:85]
	v_mov_b32_e32 v177, 0
	v_max_i32_e32 v176, 0, v89
	v_lshlrev_b32_e32 v176, 1, v176
	v_lshl_add_u64 v[178:179], v[94:95], 0, v[176:177]
	v_add_co_u32_e32 v180, vcc, s23, v178
	s_nop 1
	v_addc_co_u32_e32 v181, vcc, 0, v179, vcc
	global_load_dwordx4 v[184:187], v[178:179], off
	global_load_dwordx4 v[188:191], v[178:179], off offset:32
	global_load_dwordx4 v[192:195], v[180:181], off
	global_load_dwordx4 v[196:199], v[180:181], off offset:32
	v_max_i32_e32 v176, 0, v143
	v_lshlrev_b32_e32 v176, 1, v176
	v_lshl_add_u64 v[178:179], v[94:95], 0, v[176:177]
	v_add_co_u32_e32 v180, vcc, s23, v178
	s_nop 1
	v_addc_co_u32_e32 v181, vcc, 0, v179, vcc
	global_load_dwordx4 v[200:203], v[178:179], off
	global_load_dwordx4 v[204:207], v[180:181], off
	global_load_dwordx4 v[208:211], v[178:179], off offset:32
	global_load_dwordx4 v[212:215], v[180:181], off offset:32
	v_max_i32_e32 v176, 0, v144
	v_lshlrev_b32_e32 v176, 1, v176
	v_lshl_add_u64 v[178:179], v[94:95], 0, v[176:177]
	v_add_co_u32_e32 v180, vcc, s23, v178
	s_nop 1
	v_addc_co_u32_e32 v181, vcc, 0, v179, vcc
	global_load_dwordx4 v[216:219], v[178:179], off
	global_load_dwordx4 v[220:223], v[180:181], off
	global_load_dwordx4 v[224:227], v[178:179], off offset:32
	global_load_dwordx4 v[228:231], v[180:181], off offset:32
	v_max_i32_e32 v176, 0, v145
	v_lshlrev_b32_e32 v176, 1, v176
	v_lshl_add_u64 v[178:179], v[94:95], 0, v[176:177]
	v_add_co_u32_e32 v180, vcc, s23, v178
	s_nop 1
	v_addc_co_u32_e32 v181, vcc, 0, v179, vcc
	global_load_dwordx4 v[232:235], v[178:179], off
	global_load_dwordx4 v[240:243], v[180:181], off
	global_load_dwordx4 v[244:247], v[178:179], off offset:32
	global_load_dwordx4 v[248:251], v[180:181], off offset:32
	v_lshlrev_b32_e32 v176, 1, v32
	v_lshl_add_u64 v[178:179], v[94:95], 0, v[176:177]
	v_add_co_u32_e32 v180, vcc, s23, v178
	s_nop 1
	v_addc_co_u32_e32 v181, vcc, 0, v179, vcc
	global_load_dwordx4 v[236:239], v[178:179], off
	global_load_dwordx4 v[252:255], v[180:181], off
	global_load_dwordx4 v[168:171], v[178:179], off offset:32
	global_load_dwordx4 v[172:175], v[180:181], off offset:32
	v_lshlrev_b32_e32 v80, 1, v8
	v_pk_mul_f32 v[0:1], v[0:1], v[50:51] op_sel_hi:[1,0]
	v_pk_mul_f32 v[2:3], v[2:3], v[50:51] op_sel_hi:[1,0]
	v_lshl_add_u64 v[154:155], v[94:95], 0, v[80:81]
	v_cvt_pk_bf16_f32 v16, v0, v1
	v_cvt_pk_bf16_f32 v17, v2, v3
	v_pk_mul_f32 v[148:149], v[10:11], v[50:51] op_sel_hi:[1,0]
	v_pk_mul_f32 v[150:151], v[12:13], v[50:51] op_sel_hi:[1,0]
	v_pk_mul_f32 v[152:153], v[14:15], v[50:51] op_sel_hi:[1,0]
	v_cvt_pk_bf16_f32 v146, v146, v147
	v_cvt_pk_bf16_f32 v147, v148, v149
	v_cvt_pk_bf16_f32 v148, v150, v151
	v_cvt_pk_bf16_f32 v149, v152, v153
	v_pk_mul_f32 v[4:5], v[4:5], v[50:51] op_sel_hi:[1,0]
	v_pk_mul_f32 v[6:7], v[6:7], v[50:51] op_sel_hi:[1,0]
	v_add_co_u32_e32 v156, vcc, s23, v154
	v_cvt_pk_bf16_f32 v18, v4, v5
	v_cvt_pk_bf16_f32 v19, v6, v7
	v_addc_co_u32_e32 v157, vcc, 0, v155, vcc
	s_waitcnt vmcnt(1)
	v_mfma_f32_32x32x16_bf16 v[0:15], v[184:187], v[16:19], 0
	v_lshlrev_b32_e32 v80, 1, v33
	v_lshl_add_u64 v[154:155], v[94:95], 0, v[80:81]
	v_mul_f32_e64 v96, v96, v50
	v_mul_f32_e64 v97, v97, v50
	v_pk_mul_f32 v[100:101], v[100:101], v[50:51] op_sel_hi:[1,0]
	v_pk_mul_f32 v[104:105], v[104:105], v[50:51] op_sel_hi:[1,0]
	v_pk_mul_f32 v[116:117], v[116:117], v[50:51] op_sel_hi:[1,0]
	s_waitcnt vmcnt(1)
	v_mfma_f32_32x32x16_bf16 v[0:15], v[188:191], v[146:149], v[0:15]
	v_max_i32_e32 v33, 0, v144
	v_lshlrev_b32_e32 v80, 1, v33
	v_mul_f32_e64 v62, v62, v50
	v_mul_f32_e64 v63, v63, v50
	v_pk_mul_f32 v[66:67], v[66:67], v[50:51] op_sel_hi:[1,0]
	v_pk_mul_f32 v[74:75], v[74:75], v[50:51] op_sel_hi:[1,0]
	v_pk_mul_f32 v[78:79], v[78:79], v[50:51] op_sel_hi:[1,0]
	s_waitcnt vmcnt(1)
	v_mfma_f32_32x32x16_bf16 v[16:31], v[192:195], v[16:19], 0
	v_mul_f32_e64 v92, v92, v50
	v_mul_f32_e64 v93, v93, v50
	v_mul_f32_e64 v106, v106, v50
	v_mul_f32_e64 v107, v107, v50
	v_max_i32_e32 v33, 0, v145
	v_pk_mul_f32 v[52:53], v[52:53], v[50:51] op_sel_hi:[1,0]
	v_pk_mul_f32 v[54:55], v[54:55], v[50:51] op_sel_hi:[1,0]
	v_pk_mul_f32 v[56:57], v[56:57], v[50:51] op_sel_hi:[1,0]
	v_pk_mul_f32 v[58:59], v[58:59], v[50:51] op_sel_hi:[1,0]
	s_waitcnt vmcnt(0)
	v_mfma_f32_32x32x16_bf16 v[16:31], v[196:199], v[146:149], v[16:31]
	v_mul_f32_e64 v150, v112, v50
	v_mul_f32_e64 v151, v113, v50
	v_mul_f32_e64 v152, v114, v50
	v_mul_f32_e64 v153, v115, v50
	v_pk_mul_f32 v[146:147], v[108:109], v[50:51] op_sel_hi:[1,0]
	v_cvt_pk_bf16_f32 v108, v96, v97
	v_add_co_u32_e32 v96, vcc, s23, v154
	v_pk_mul_f32 v[148:149], v[110:111], v[50:51] op_sel_hi:[1,0]
	v_cvt_pk_bf16_f32 v109, v100, v101
	v_cvt_pk_bf16_f32 v110, v104, v105
	v_cvt_pk_bf16_f32 v111, v146, v147
	v_addc_co_u32_e32 v97, vcc, 0, v155, vcc
	s_waitcnt vmcnt(0)
; #define MFMA32(a, b, c) __builtin_amdgcn_mfma_f32_32x32x16_bf16((a), (b), (c), 0, 0, 0)
; DI float xor32_add(float x) { auto r = __builtin_amdgcn_permlane32_swap(__float_as_uint(x), __float_as_uint(x), false, false); return __uint_as_float(r[0]) + __uint_as_float(r[1]); }
; DI void store_o(bf16_t* o, float* ssq, int token, int colbase, int slot, const f32x16 (&oacc)[2], int h) {
;   float ss = 0.f;
; #pragma unroll
;   for (int dt = 0; dt < 2; ++dt)
; #pragma unroll
;     for (int g = 0; g < 4; ++g) {
;       float a = oacc[dt][4 * g], b = oacc[dt][4 * g + 1], c = oacc[dt][4 * g + 2], d = oacc[dt][4 * g + 3];
;       ss += a * a + b * b + c * c + d * d;
;       *(uint2*)(o + (size_t)token * 1024 + colbase + 32 * dt + 8 * g + 4 * h) = make_uint2(pack2(a, b), pack2(c, d));
;     }
;   ss = xor32_add(ss);
;   if (h == 0) ssq[(size_t)token * 16 + slot] = ss;
; DI void swa_item(const Params& p, int item, int lane) {
;     ...
; #pragma unroll
;   for (int t = 0; t < 5; ++t) {
;     const int pos0 = (n - 1) * 128 + 32 * (w + t), pc = pos0 < 0 ? 0 : pos0;
; #pragma unroll
;     for (int r = 0; r < 16; ++r) sc[t][r] *= inv;
; #pragma unroll
;     for (int s2 = 0; s2 < 2; ++s2) {
;       bf16x8 pb = packp(sc[t], s2);
; #pragma unroll
;       for (int dt = 0; dt < 2; ++dt)
;         oacc[dt] = MFMA32(ldg8(vbase + (size_t)(32 * dt) * SEQ + pc + 16 * s2), pb, oacc[dt]);
;     }
;   }
;   store_o(o, ssq, token, hq * 64, hq, oacc, h);
	v_mfma_f32_32x32x16_bf16 v[0:15], v[200:203], v[108:111], v[0:15]
	v_mul_f32_e64 v104, v98, v50
	v_mul_f32_e64 v105, v99, v50
	v_cvt_pk_bf16_f32 v98, v74, v75
	v_cvt_pk_bf16_f32 v99, v78, v79
	v_cvt_pk_bf16_f32 v52, v52, v53
	v_cvt_pk_bf16_f32 v53, v54, v55
	v_cvt_pk_bf16_f32 v54, v56, v57
	s_waitcnt vmcnt(0)
	v_mfma_f32_32x32x16_bf16 v[16:31], v[204:207], v[108:111], v[16:31]
	v_cvt_pk_bf16_f32 v108, v148, v149
	v_cvt_pk_bf16_f32 v109, v150, v151
	v_cvt_pk_bf16_f32 v110, v152, v153
	v_cvt_pk_bf16_f32 v111, v116, v117
	v_cvt_pk_bf16_f32 v55, v58, v59
	v_pk_mul_f32 v[60:61], v[60:61], v[50:51] op_sel_hi:[1,0]
	s_waitcnt vmcnt(0)
	v_mfma_f32_32x32x16_bf16 v[0:15], v[208:211], v[108:111], v[0:15]
	v_cvt_pk_bf16_f32 v96, v62, v63
	v_cvt_pk_bf16_f32 v97, v66, v67
	v_mul_f32_e64 v66, v76, v50
	v_mul_f32_e64 v67, v77, v50
	v_pk_mul_f32 v[34:35], v[34:35], v[50:51] op_sel_hi:[1,0]
	v_pk_mul_f32 v[36:37], v[36:37], v[50:51] op_sel_hi:[1,0]
	v_pk_mul_f32 v[38:39], v[38:39], v[50:51] op_sel_hi:[1,0]
	s_waitcnt vmcnt(0)
	v_mfma_f32_32x32x16_bf16 v[16:31], v[212:215], v[108:111], v[16:31]
	v_lshl_add_u64 v[110:111], v[94:95], 0, v[80:81]
	v_mul_f32_e64 v108, v102, v50
	v_mul_f32_e64 v109, v103, v50
	v_add_co_u32_e32 v62, vcc, s23, v110
	v_lshlrev_b32_e32 v80, 1, v33
	s_nop 0
	v_addc_co_u32_e32 v63, vcc, 0, v111, vcc
	s_waitcnt vmcnt(0)
	v_mfma_f32_32x32x16_bf16 v[0:15], v[216:219], v[96:99], v[0:15]
	v_mov_b32_e32 v33, v81
	v_mul_f32_e64 v40, v40, v50
	v_mul_f32_e64 v41, v41, v50
	v_mul_f32_e64 v42, v42, v50
	v_mul_f32_e64 v43, v43, v50
	v_pk_mul_f32 v[44:45], v[44:45], v[50:51] op_sel_hi:[1,0]
	v_pk_mul_f32 v[46:47], v[46:47], v[50:51] op_sel_hi:[1,0]
	v_pk_mul_f32 v[48:49], v[48:49], v[50:51] op_sel_hi:[1,0]
	s_waitcnt vmcnt(0)
	v_mfma_f32_32x32x16_bf16 v[16:31], v[220:223], v[96:99], v[16:31]
	v_cvt_pk_bf16_f32 v96, v92, v93
	v_cvt_pk_bf16_f32 v97, v104, v105
	v_cvt_pk_bf16_f32 v98, v108, v109
	v_cvt_pk_bf16_f32 v99, v106, v107
	v_mov_b32_e32 v91, v81
	s_waitcnt vmcnt(0)
	v_mfma_f32_32x32x16_bf16 v[0:15], v[224:227], v[96:99], v[0:15]
	v_mul_f32_e64 v62, v64, v50
	v_mul_f32_e64 v63, v65, v50
	v_mul_f32_e64 v64, v72, v50
	v_mul_f32_e64 v65, v73, v50
	v_lshl_add_u64 v[72:73], v[94:95], 0, v[80:81]
	v_add_co_u32_e32 v74, vcc, s23, v72
	v_lshl_add_u64 v[50:51], v[32:33], 1, v[94:95]
	s_nop 0
	v_addc_co_u32_e32 v75, vcc, 0, v73, vcc
	v_cvt_pk_bf16_f32 v32, v34, v35
	v_cvt_pk_bf16_f32 v33, v36, v37
	v_cvt_pk_bf16_f32 v34, v38, v39
	s_waitcnt vmcnt(1)
	v_mfma_f32_32x32x16_bf16 v[0:15], v[232:235], v[52:55], v[0:15]
	v_cvt_pk_bf16_f32 v35, v40, v41
	v_add_co_u32_e32 v40, vcc, s23, v50
	v_mov_b32_e32 v80, v69
	s_nop 0
	v_addc_co_u32_e32 v41, vcc, 0, v51, vcc
	v_mfma_f32_32x32x16_bf16 v[16:31], v[228:231], v[96:99], v[16:31]
	s_waitcnt vmcnt(0)
	v_mfma_f32_32x32x16_bf16 v[16:31], v[240:243], v[52:55], v[16:31]
	v_cvt_pk_bf16_f32 v52, v60, v61
	v_cvt_pk_bf16_f32 v53, v62, v63
	v_cvt_pk_bf16_f32 v54, v64, v65
	v_cvt_pk_bf16_f32 v55, v66, v67
	s_waitcnt vmcnt(0)
	s_nop 0
	v_mfma_f32_32x32x16_bf16 v[0:15], v[244:247], v[52:55], v[0:15]
	v_mfma_f32_32x32x16_bf16 v[0:15], v[236:239], v[32:35], v[0:15]
	s_waitcnt vmcnt(1)
	v_mfma_f32_32x32x16_bf16 v[16:31], v[248:251], v[52:55], v[16:31]
	s_waitcnt vmcnt(0)
	v_mfma_f32_32x32x16_bf16 v[16:31], v[252:255], v[32:35], v[16:31]
	v_cvt_pk_bf16_f32 v32, v42, v43
	v_cvt_pk_bf16_f32 v33, v44, v45
	v_cvt_pk_bf16_f32 v34, v46, v47
	v_cvt_pk_bf16_f32 v35, v48, v49
	s_waitcnt vmcnt(0)
	s_nop 0
	v_mfma_f32_32x32x16_bf16 v[0:15], v[168:171], v[32:35], v[0:15]
	s_waitcnt vmcnt(0)
	v_mfma_f32_32x32x16_bf16 v[16:31], v[172:175], v[32:35], v[16:31]
	v_lshlrev_b64 v[32:33], 11, v[80:81]
	v_lshl_add_u64 v[32:33], s[50:51], 0, v[32:33]
	v_lshl_add_u64 v[32:33], v[32:33], 0, v[70:71]
	s_nop 5
	v_mul_f32_e32 v34, v1, v1
	v_lshl_add_u64 v[32:33], v[32:33], 0, v[90:91]
	v_fmac_f32_e32 v34, v0, v0
	v_cvt_pk_bf16_f32 v0, v0, v1
	v_cvt_pk_bf16_f32 v1, v2, v3
	global_store_dwordx2 v[32:33], v[0:1], off
	v_mul_f32_e32 v0, v5, v5
	v_fmac_f32_e32 v0, v4, v4
	v_fmac_f32_e32 v34, v2, v2
	v_fmac_f32_e32 v0, v6, v6
	v_fmac_f32_e32 v34, v3, v3
	v_fmac_f32_e32 v0, v7, v7
	v_add_f32_e32 v2, v34, v0
	v_cvt_pk_bf16_f32 v0, v4, v5
	v_cvt_pk_bf16_f32 v1, v6, v7
	global_store_dwordx2 v[32:33], v[0:1], off offset:16
	v_mul_f32_e32 v0, v9, v9
	v_fmac_f32_e32 v0, v8, v8
	v_fmac_f32_e32 v0, v10, v10
	v_fmac_f32_e32 v0, v11, v11
	v_add_f32_e32 v2, v0, v2
	v_cvt_pk_bf16_f32 v0, v8, v9
	v_cvt_pk_bf16_f32 v1, v10, v11
	global_store_dwordx2 v[32:33], v[0:1], off offset:32
	v_mul_f32_e32 v0, v13, v13
	v_fmac_f32_e32 v0, v12, v12
	v_fmac_f32_e32 v0, v14, v14
	v_fmac_f32_e32 v0, v15, v15
	v_add_f32_e32 v2, v0, v2
	v_cvt_pk_bf16_f32 v0, v12, v13
	v_cvt_pk_bf16_f32 v1, v14, v15
	global_store_dwordx2 v[32:33], v[0:1], off offset:48
	v_mul_f32_e32 v0, v17, v17
	v_fmac_f32_e32 v0, v16, v16
	v_fmac_f32_e32 v0, v18, v18
	v_fmac_f32_e32 v0, v19, v19
	v_add_f32_e32 v2, v0, v2
	v_cvt_pk_bf16_f32 v0, v16, v17
	v_cvt_pk_bf16_f32 v1, v18, v19
	global_store_dwordx2 v[32:33], v[0:1], off offset:64
	v_mul_f32_e32 v0, v21, v21
	v_fmac_f32_e32 v0, v20, v20
	v_fmac_f32_e32 v0, v22, v22
	v_fmac_f32_e32 v0, v23, v23
	v_add_f32_e32 v2, v0, v2
	v_cvt_pk_bf16_f32 v0, v20, v21
	v_cvt_pk_bf16_f32 v1, v22, v23
	global_store_dwordx2 v[32:33], v[0:1], off offset:80
	v_mul_f32_e32 v0, v25, v25
	v_fmac_f32_e32 v0, v24, v24
	v_fmac_f32_e32 v0, v26, v26
	v_fmac_f32_e32 v0, v27, v27
	v_add_f32_e32 v2, v0, v2
	v_cvt_pk_bf16_f32 v0, v24, v25
	v_cvt_pk_bf16_f32 v1, v26, v27
	global_store_dwordx2 v[32:33], v[0:1], off offset:96
	v_mul_f32_e32 v0, v29, v29
	v_fmac_f32_e32 v0, v28, v28
	v_fmac_f32_e32 v0, v30, v30
	v_fmac_f32_e32 v0, v31, v31
	v_add_f32_e32 v0, v0, v2
	v_mov_b32_e32 v1, v0
	v_cvt_pk_bf16_f32 v2, v28, v29
	v_cvt_pk_bf16_f32 v3, v30, v31
	v_permlane32_swap_b32_e32 v0, v1
	global_store_dwordx2 v[32:33], v[2:3], off offset:112
	s_and_saveexec_b64 s[0:1], s[38:39]
	s_cbranch_execz .LBB0_249
	v_add_f32_e32 v2, v0, v1
	v_lshlrev_b64 v[0:1], 6, v[80:81]
	v_lshl_add_u64 v[0:1], s[52:53], 0, v[0:1]
	v_mov_b32_e32 v69, v81
	v_lshl_add_u64 v[0:1], v[0:1], 0, v[68:69]
	global_store_dword v[0:1], v2, off
